# prompt attention: QK accumulators initialised to -running max so the common softmax path has no per-element subtraction (rare path keeps subtract/rescale)
# baseline (speedup 1.0000x reference)
;     ...
;     float mrun = -INFINITY, lrun = 0.f;
;     ...
;         gload(0); lstore(0); if (ntiles > 1) gload(1);
;         __syncthreads();
;         for (int t = 0; t < ntiles; ++t) { const int cur = t & 1;
.LBB0_1906:
	v_sub_f32_e32 v255, 0, v224
	s_lshl_b32 s0, s15, 2
	v_ashrrev_i32_e32 v185, 31, v184
	v_mul_u32_u24_e32 v14, 0x88, v208
	s_add_i32 s13, s13, 5
	s_add_i32 s46, s16, 0x80
	s_sub_i32 s15, 0, s0
	s_movk_i32 s16, 0xff80
	s_waitcnt lgkmcnt(0)
	s_barrier

; #define MFMA32(a, b, c) __builtin_amdgcn_mfma_f32_32x32x16_bf16((a), (b), (c), 0, 0, 0)
; DI float xhalf_max(float v) { const auto r = __builtin_amdgcn_permlane32_swap(__float_as_uint(v), __float_as_uint(v), false, false); return fmaxf(__uint_as_float(r[0]), __uint_as_float(r[1])); }
;     ...
; #pragma unroll
;         for (int ks = 0; ks < NKS; ++ks) { const bf16x8 a0 = *(const bf16x8*)(Kt + lr * KSTR + 16 * ks + 8 * hi), a1 = *(const bf16x8*)(Kt + (32 + lr) * KSTR + 16 * ks + 8 * hi);
;             bf16x8 qq;
;             if (QREG == 1) qq = qf[ks];
;             else if (QREG == 2) qq = 16 * ks < DN ? qf[ks < NQF ? ks : 0] : *(const bf16x8*)(qr_row + (16 * ks - DN) + 8 * hi);
;             else qq = 16 * ks < DN ? *(const bf16x8*)(qa_row + 16 * ks + 8 * hi) : qf[(16 * ks - DN) / 16 < NQF ? (16 * ks - DN) / 16 : 0];
;             s0 = MFMA32(a0, qq, s0); s1 = MFMA32(a1, qq, s1);
;             if ((ks & 3) == 3) __builtin_amdgcn_sched_barrier(0); }
;         if (t == 0) {
; #pragma unroll
;             for (int i = 0; i < 16; ++i) { if (i >= 8) s0[i] = -INFINITY; s1[i] = -INFINITY; } }
;         float mx = s0[0];
; #pragma unroll
;         for (int i = 1; i < 16; ++i) mx = fmaxf(mx, s0[i]);
; #pragma unroll
;         for (int i = 0; i < 16; ++i) mx = fmaxf(mx, s1[i]);
;         mx = xhalf_max(mx);
;         const float mnew = fmaxf(mrun, mx), alpha = __builtin_amdgcn_exp2f(mrun - mnew);
;         const bool resc = __builtin_amdgcn_ballot_w64(mnew != mrun) != 0ull; mrun = mnew;
.LBB0_1910:
	s_mul_i32 s17, s17, 0xa800
	s_add_i32 s0, s17, 0
	v_lshlrev_b32_e32 v0, 1, v186
	v_add3_u32 v0, s0, v189, v0
	ds_read_b128 v[2:5], v0
	ds_read_b128 v[6:9], v0 offset:12800
	ds_read_b128 v[10:13], v0 offset:32
	ds_read_b128 v[226:229], v0 offset:12832
	ds_read_b128 v[230:233], v0 offset:64
	ds_read_b128 v[238:241], v0 offset:12864
	v_add3_u32 v225, s0, v14, v222
	v_add_u32_e32 v225, 0x6400, v225
	v_add_u32_e32 v234, 0x1100, v225
	v_add_u32_e32 v235, 0x2200, v225
	v_add_u32_e32 v236, 0x3300, v225
	v_mov_b32_e32 v80, v255
	v_mov_b32_e32 v81, v255
	v_mov_b32_e32 v82, v255
	v_mov_b32_e32 v83, v255
	v_mov_b32_e32 v84, v255
	v_mov_b32_e32 v85, v255
	v_mov_b32_e32 v86, v255
	v_mov_b32_e32 v87, v255
	v_mov_b32_e32 v88, v255
	v_mov_b32_e32 v89, v255
	v_mov_b32_e32 v90, v255
	v_mov_b32_e32 v91, v255
	v_mov_b32_e32 v92, v255
	v_mov_b32_e32 v93, v255
	v_mov_b32_e32 v94, v255
	v_mov_b32_e32 v95, v255
	v_mov_b32_e32 v96, v255
	v_mov_b32_e32 v97, v255
	v_mov_b32_e32 v98, v255
	v_mov_b32_e32 v99, v255
	v_mov_b32_e32 v100, v255
	v_mov_b32_e32 v101, v255
	v_mov_b32_e32 v102, v255
	v_mov_b32_e32 v103, v255
	v_mov_b32_e32 v104, v255
	v_mov_b32_e32 v105, v255
	v_mov_b32_e32 v106, v255
	v_mov_b32_e32 v107, v255
	v_mov_b32_e32 v108, v255
	v_mov_b32_e32 v109, v255
	v_mov_b32_e32 v110, v255
	v_mov_b32_e32 v111, v255
	s_waitcnt lgkmcnt(5)
	v_mfma_f32_32x32x16_bf16 v[80:95], v[2:5], v[112:115], v[80:95]
	ds_read_b128 v[2:5], v0 offset:96
	s_waitcnt lgkmcnt(5)
	v_mfma_f32_32x32x16_bf16 v[96:111], v[6:9], v[112:115], v[96:111]
	ds_read_b128 v[6:9], v0 offset:12896
	s_waitcnt lgkmcnt(5)
	v_mfma_f32_32x32x16_bf16 v[80:95], v[10:13], v[116:119], v[80:95]
	ds_read_b128 v[10:13], v0 offset:128
	s_waitcnt lgkmcnt(5)
	v_mfma_f32_32x32x16_bf16 v[96:111], v[226:229], v[116:119], v[96:111]
	ds_read_b128 v[226:229], v0 offset:12928
	s_waitcnt lgkmcnt(5)
	v_mfma_f32_32x32x16_bf16 v[80:95], v[230:233], v[120:123], v[80:95]
	ds_read_b128 v[230:233], v0 offset:160
	s_waitcnt lgkmcnt(5)
	v_mfma_f32_32x32x16_bf16 v[96:111], v[238:241], v[120:123], v[96:111]
	ds_read_b128 v[238:241], v0 offset:12960
	s_waitcnt lgkmcnt(5)
	v_mfma_f32_32x32x16_bf16 v[80:95], v[2:5], v[124:127], v[80:95]
	ds_read_b128 v[2:5], v0 offset:192
	s_waitcnt lgkmcnt(5)
	v_mfma_f32_32x32x16_bf16 v[96:111], v[6:9], v[124:127], v[96:111]
	ds_read_b128 v[6:9], v0 offset:12992
	s_waitcnt lgkmcnt(5)
	v_mfma_f32_32x32x16_bf16 v[80:95], v[10:13], v[128:131], v[80:95]
	ds_read_b128 v[10:13], v0 offset:224
	s_waitcnt lgkmcnt(5)
	v_mfma_f32_32x32x16_bf16 v[96:111], v[226:229], v[128:131], v[96:111]
	ds_read_b128 v[226:229], v0 offset:13024
	s_waitcnt lgkmcnt(5)
	v_mfma_f32_32x32x16_bf16 v[80:95], v[230:233], v[132:135], v[80:95]
	ds_read_b128 v[230:233], v0 offset:256
	s_waitcnt lgkmcnt(5)
	v_mfma_f32_32x32x16_bf16 v[96:111], v[238:241], v[132:135], v[96:111]
	ds_read_b128 v[238:241], v0 offset:13056
	s_waitcnt lgkmcnt(5)
	v_mfma_f32_32x32x16_bf16 v[80:95], v[2:5], v[136:139], v[80:95]
	ds_read_b128 v[2:5], v0 offset:288
	s_waitcnt lgkmcnt(5)
	v_mfma_f32_32x32x16_bf16 v[96:111], v[6:9], v[136:139], v[96:111]
	ds_read_b128 v[6:9], v0 offset:13088
	s_waitcnt lgkmcnt(5)
	v_mfma_f32_32x32x16_bf16 v[80:95], v[10:13], v[140:143], v[80:95]
	ds_read_b128 v[10:13], v0 offset:320
	s_waitcnt lgkmcnt(5)
	v_mfma_f32_32x32x16_bf16 v[96:111], v[226:229], v[140:143], v[96:111]
	ds_read_b128 v[226:229], v0 offset:13120
	s_waitcnt lgkmcnt(5)
	v_mfma_f32_32x32x16_bf16 v[80:95], v[230:233], v[144:147], v[80:95]
	ds_read_b128 v[230:233], v0 offset:352
	s_waitcnt lgkmcnt(5)
	v_mfma_f32_32x32x16_bf16 v[96:111], v[238:241], v[144:147], v[96:111]
	ds_read_b128 v[238:241], v0 offset:13152
	s_waitcnt lgkmcnt(5)
	v_mfma_f32_32x32x16_bf16 v[80:95], v[2:5], v[148:151], v[80:95]
	ds_read2_b64 v[242:245], v225 offset1:2
	s_waitcnt lgkmcnt(5)
	v_mfma_f32_32x32x16_bf16 v[96:111], v[6:9], v[148:151], v[96:111]
	s_waitcnt lgkmcnt(4)
	v_mfma_f32_32x32x16_bf16 v[80:95], v[10:13], v[152:155], v[80:95]
	s_waitcnt lgkmcnt(3)
	v_mfma_f32_32x32x16_bf16 v[96:111], v[226:229], v[152:155], v[96:111]
	ds_read2_b64 v[226:229], v225 offset0:4 offset1:6
	s_waitcnt lgkmcnt(3)
	v_mfma_f32_32x32x16_bf16 v[80:95], v[230:233], v[156:159], v[80:95]
	ds_read2_b64 v[230:233], v225 offset0:8 offset1:10
	s_waitcnt lgkmcnt(3)
	v_mfma_f32_32x32x16_bf16 v[96:111], v[238:241], v[156:159], v[96:111]
	ds_read2_b64 v[238:241], v225 offset0:12 offset1:14
	s_nop 8
	v_max_f32_e32 v0, v81, v81
	v_max_f32_e32 v2, v80, v80
	v_max_f32_e32 v0, v2, v0
	v_max3_f32 v0, v0, v82, v83
	v_max3_f32 v0, v0, v84, v85
	v_max3_f32 v0, v0, v86, v87
	v_max3_f32 v0, v0, v88, v89
	v_max3_f32 v0, v0, v90, v91
	v_max3_f32 v0, v0, v92, v93
	v_max3_f32 v0, v0, v94, v95
	v_max3_f32 v0, v0, v96, v97
	v_max3_f32 v0, v0, v98, v99
	v_max3_f32 v0, v0, v100, v101
	v_max3_f32 v0, v0, v102, v103
	v_max3_f32 v0, v0, v104, v105
	v_max3_f32 v0, v0, v106, v107
	v_max3_f32 v0, v0, v108, v109
	v_max3_f32 v0, v0, v110, v111
	v_mov_b32_e32 v2, v0
	s_nop 1
	v_permlane32_swap_b32_e32 v0, v2
	v_max_f32_e32 v2, v0, v2
	v_cmp_lt_f32_e32 vcc, 0x41000000, v2
	s_cbranch_vccz .Lfz_fast
;     ...
;         const float mnew = fmaxf(mrun, mx), alpha = __builtin_amdgcn_exp2f(mrun - mnew);
;         const bool resc = __builtin_amdgcn_ballot_w64(mnew != mrun) != 0ull; mrun = mnew;
;         float ps = 0.f;
; #pragma unroll
;         for (int i = 0; i < 16; ++i) { s0[i] = __builtin_amdgcn_exp2f(s0[i] - mnew); s1[i] = __builtin_amdgcn_exp2f(s1[i] - mnew); ps += s0[i] + s1[i]; }
;         lrun = lrun * alpha + ps;
;         if (resc) {
; #pragma unroll
;             for (int d = 0; d < 4; ++d)
; #pragma unroll
;                 for (int i = 0; i < 16; ++i) oacc[d][i] *= alpha; }
;         bf16x8 pf[4]; pf[0] = packs(s0, 0); pf[1] = packs(s0, 1); pf[2] = packs(s1, 0); pf[3] = packs(s1, 1);
	v_cndmask_b32_e32 v15, 0, v2, vcc
	v_sub_f32_e32 v0, 0, v15
	v_exp_f32_e32 v0, v0
	v_add_f32_e32 v224, v224, v15
	v_sub_f32_e32 v255, 0, v224
	v_pk_mul_f32 v[46:47], v[46:47], v[0:1] op_sel_hi:[1,0]
	v_pk_mul_f32 v[44:45], v[44:45], v[0:1] op_sel_hi:[1,0]
	v_pk_mul_f32 v[42:43], v[42:43], v[0:1] op_sel_hi:[1,0]
	v_pk_mul_f32 v[40:41], v[40:41], v[0:1] op_sel_hi:[1,0]
	v_pk_mul_f32 v[38:39], v[38:39], v[0:1] op_sel_hi:[1,0]
	v_pk_mul_f32 v[36:37], v[36:37], v[0:1] op_sel_hi:[1,0]
	v_pk_mul_f32 v[34:35], v[34:35], v[0:1] op_sel_hi:[1,0]
	v_pk_mul_f32 v[32:33], v[32:33], v[0:1] op_sel_hi:[1,0]
	v_pk_mul_f32 v[78:79], v[78:79], v[0:1] op_sel_hi:[1,0]
	v_pk_mul_f32 v[76:77], v[76:77], v[0:1] op_sel_hi:[1,0]
	v_pk_mul_f32 v[74:75], v[74:75], v[0:1] op_sel_hi:[1,0]
	v_pk_mul_f32 v[72:73], v[72:73], v[0:1] op_sel_hi:[1,0]
	v_pk_mul_f32 v[70:71], v[70:71], v[0:1] op_sel_hi:[1,0]
	v_pk_mul_f32 v[68:69], v[68:69], v[0:1] op_sel_hi:[1,0]
	v_pk_mul_f32 v[66:67], v[66:67], v[0:1] op_sel_hi:[1,0]
	v_pk_mul_f32 v[64:65], v[64:65], v[0:1] op_sel_hi:[1,0]
	v_pk_mul_f32 v[62:63], v[62:63], v[0:1] op_sel_hi:[1,0]
	v_pk_mul_f32 v[60:61], v[60:61], v[0:1] op_sel_hi:[1,0]
	v_pk_mul_f32 v[58:59], v[58:59], v[0:1] op_sel_hi:[1,0]
	v_pk_mul_f32 v[56:57], v[56:57], v[0:1] op_sel_hi:[1,0]
	v_pk_mul_f32 v[54:55], v[54:55], v[0:1] op_sel_hi:[1,0]
	v_pk_mul_f32 v[52:53], v[52:53], v[0:1] op_sel_hi:[1,0]
	v_pk_mul_f32 v[50:51], v[50:51], v[0:1] op_sel_hi:[1,0]
	v_pk_mul_f32 v[48:49], v[48:49], v[0:1] op_sel_hi:[1,0]
	v_pk_mul_f32 v[30:31], v[30:31], v[0:1] op_sel_hi:[1,0]
	v_pk_mul_f32 v[28:29], v[28:29], v[0:1] op_sel_hi:[1,0]
	v_pk_mul_f32 v[26:27], v[26:27], v[0:1] op_sel_hi:[1,0]
	v_pk_mul_f32 v[24:25], v[24:25], v[0:1] op_sel_hi:[1,0]
	v_pk_mul_f32 v[22:23], v[22:23], v[0:1] op_sel_hi:[1,0]
	v_pk_mul_f32 v[20:21], v[20:21], v[0:1] op_sel_hi:[1,0]
	v_pk_mul_f32 v[18:19], v[18:19], v[0:1] op_sel_hi:[1,0]
	v_pk_mul_f32 v[16:17], v[16:17], v[0:1] op_sel_hi:[1,0]
	v_sub_f32_e32 v2, v80, v15
	v_sub_f32_e32 v3, v96, v15
	v_exp_f32_e32 v2, v2
	v_exp_f32_e32 v3, v3
	v_sub_f32_e32 v5, v81, v15
	v_sub_f32_e32 v6, v97, v15
	v_exp_f32_e32 v5, v5
	v_exp_f32_e32 v6, v6
	v_add_f32_e32 v4, v2, v3
	v_add_f32_e32 v4, 0, v4
	v_sub_f32_e32 v8, v98, v15
	v_add_f32_e32 v7, v5, v6
	v_add_f32_e32 v4, v7, v4
	v_sub_f32_e32 v7, v82, v15
	v_exp_f32_e32 v7, v7
	v_exp_f32_e32 v8, v8
	v_sub_f32_e32 v10, v99, v15
	v_exp_f32_e32 v96, v10
	v_sub_f32_e32 v11, v100, v15
	v_add_f32_e32 v9, v7, v8
	v_add_f32_e32 v4, v9, v4
	v_sub_f32_e32 v9, v83, v15
	v_exp_f32_e32 v9, v9
	v_sub_f32_e32 v12, v101, v15
	v_sub_f32_e32 v13, v102, v15
	v_sub_f32_e32 v80, v103, v15
	v_add_f32_e32 v10, v9, v96
	v_add_f32_e32 v4, v10, v4
	v_sub_f32_e32 v10, v84, v15
	v_exp_f32_e32 v10, v10
	v_exp_f32_e32 v84, v11
	v_cvt_pk_bf16_f32 v81, v7, v9
	v_cvt_pk_bf16_f32 v7, v8, v96
	v_cvt_pk_bf16_f32 v6, v3, v6
	v_add_f32_e32 v11, v10, v84
	v_add_f32_e32 v4, v11, v4
	v_sub_f32_e32 v11, v85, v15
	v_exp_f32_e32 v11, v11
	v_exp_f32_e32 v85, v12
	v_cvt_pk_bf16_f32 v82, v10, v11
	v_add_f32_e32 v12, v11, v85
	v_add_f32_e32 v4, v12, v4
	v_sub_f32_e32 v12, v86, v15
	v_exp_f32_e32 v12, v12
	v_exp_f32_e32 v86, v13
	v_cvt_pk_bf16_f32 v8, v84, v85
	v_add_f32_e32 v13, v12, v86
	v_add_f32_e32 v4, v13, v4
	v_sub_f32_e32 v13, v87, v15
	v_exp_f32_e32 v13, v13
	v_exp_f32_e32 v87, v80
	v_cvt_pk_bf16_f32 v83, v12, v13
	v_add_f32_e32 v80, v13, v87
	v_add_f32_e32 v4, v80, v4
	v_sub_f32_e32 v80, v88, v15
	v_exp_f32_e32 v88, v80
	v_sub_f32_e32 v80, v104, v15
	v_exp_f32_e32 v97, v80
	v_cvt_pk_bf16_f32 v9, v86, v87
	v_add_f32_e32 v80, v88, v97
	v_add_f32_e32 v4, v80, v4
	v_sub_f32_e32 v80, v89, v15
	v_exp_f32_e32 v89, v80
	v_sub_f32_e32 v80, v105, v15
	v_exp_f32_e32 v98, v80
	v_cvt_pk_bf16_f32 v10, v88, v89
	v_add_f32_e32 v80, v89, v98
	v_add_f32_e32 v4, v80, v4
	v_sub_f32_e32 v80, v90, v15
	v_exp_f32_e32 v90, v80
	v_sub_f32_e32 v80, v106, v15
	v_exp_f32_e32 v99, v80
	s_nop 0
	v_add_f32_e32 v80, v90, v99
	v_add_f32_e32 v4, v80, v4
	v_sub_f32_e32 v80, v91, v15
	v_exp_f32_e32 v91, v80
	v_sub_f32_e32 v80, v107, v15
	v_exp_f32_e32 v100, v80
	v_cvt_pk_bf16_f32 v11, v90, v91
	v_add_f32_e32 v80, v91, v100
	v_add_f32_e32 v4, v80, v4
	v_sub_f32_e32 v80, v92, v15
	v_exp_f32_e32 v92, v80
	v_sub_f32_e32 v80, v108, v15
	v_exp_f32_e32 v101, v80
	v_cvt_pk_bf16_f32 v3, v99, v100
	v_add_f32_e32 v80, v92, v101
	v_add_f32_e32 v4, v80, v4
	v_sub_f32_e32 v80, v93, v15
	v_exp_f32_e32 v93, v80
	v_sub_f32_e32 v80, v109, v15
	v_exp_f32_e32 v102, v80
	v_cvt_pk_bf16_f32 v12, v92, v93
	v_add_f32_e32 v80, v93, v102
	v_add_f32_e32 v4, v80, v4
	v_sub_f32_e32 v80, v94, v15
	v_exp_f32_e32 v94, v80
	v_sub_f32_e32 v80, v110, v15
	v_exp_f32_e32 v103, v80
	s_nop 0
	v_add_f32_e32 v80, v94, v103
	v_add_f32_e32 v4, v80, v4
	v_sub_f32_e32 v80, v95, v15
	v_exp_f32_e32 v95, v80
	v_sub_f32_e32 v80, v111, v15
	v_exp_f32_e32 v104, v80
	v_cvt_pk_bf16_f32 v13, v94, v95
	v_add_f32_e32 v80, v95, v104
	v_add_f32_e32 v105, v80, v4
	v_fmac_f32_e32 v105, v223, v0
	s_branch .Lfz_join
; #define MFMA32(a, b, c) __builtin_amdgcn_mfma_f32_32x32x16_bf16((a), (b), (c), 0, 0, 0)
;     ...
; #pragma unroll
;         for (int i = 0; i < 16; ++i) { s0[i] = __builtin_amdgcn_exp2f(s0[i] - mnew); s1[i] = __builtin_amdgcn_exp2f(s1[i] - mnew); ps += s0[i] + s1[i]; }
;         lrun = lrun * alpha + ps;
;         if (resc) {
; #pragma unroll
;             for (int d = 0; d < 4; ++d)
; #pragma unroll
;                 for (int i = 0; i < 16; ++i) oacc[d][i] *= alpha; }
;         bf16x8 pf[4]; pf[0] = packs(s0, 0); pf[1] = packs(s0, 1); pf[2] = packs(s1, 0); pf[3] = packs(s1, 1);
; #pragma unroll
;         for (int d = 0; d < 4; ++d)
; #pragma unroll
;             for (int ks = 0; ks < 4; ++ks) { const bf16x8 a = ld_perm(Vt + (32 * d + lr) * VSTR + 16 * ks + 4 * hi); oacc[d] = MFMA32(a, pf[ks], oacc[d]); if (ks == 3) __builtin_amdgcn_sched_barrier(0); }
.Lfz_fast:
	v_exp_f32_e32 v2, v80
	v_exp_f32_e32 v3, v96
	v_exp_f32_e32 v5, v81
	v_exp_f32_e32 v6, v97
	v_add_f32_e32 v4, v2, v3
	v_add_f32_e32 v4, 0, v4
	v_add_f32_e32 v7, v5, v6
	v_add_f32_e32 v4, v7, v4
	v_exp_f32_e32 v7, v82
	v_exp_f32_e32 v8, v98
	v_exp_f32_e32 v96, v99
	v_add_f32_e32 v9, v7, v8
	v_add_f32_e32 v4, v9, v4
	v_exp_f32_e32 v9, v83
	v_add_f32_e32 v10, v9, v96
	v_add_f32_e32 v4, v10, v4
	v_exp_f32_e32 v10, v84
	v_exp_f32_e32 v84, v100
	v_cvt_pk_bf16_f32 v81, v7, v9
	v_cvt_pk_bf16_f32 v7, v8, v96
	v_cvt_pk_bf16_f32 v6, v3, v6
	v_add_f32_e32 v11, v10, v84
	v_add_f32_e32 v4, v11, v4
	v_exp_f32_e32 v11, v85
	v_exp_f32_e32 v85, v101
	v_cvt_pk_bf16_f32 v82, v10, v11
	v_add_f32_e32 v12, v11, v85
	v_add_f32_e32 v4, v12, v4
	v_exp_f32_e32 v12, v86
	v_exp_f32_e32 v86, v102
	v_cvt_pk_bf16_f32 v8, v84, v85
	v_add_f32_e32 v13, v12, v86
	v_add_f32_e32 v4, v13, v4
	v_exp_f32_e32 v13, v87
	v_exp_f32_e32 v87, v103
	v_cvt_pk_bf16_f32 v83, v12, v13
	v_add_f32_e32 v80, v13, v87
	v_add_f32_e32 v4, v80, v4
	v_exp_f32_e32 v88, v88
	v_exp_f32_e32 v97, v104
	v_cvt_pk_bf16_f32 v9, v86, v87
	v_add_f32_e32 v80, v88, v97
	v_add_f32_e32 v4, v80, v4
	v_exp_f32_e32 v89, v89
	v_exp_f32_e32 v98, v105
	v_cvt_pk_bf16_f32 v10, v88, v89
	v_add_f32_e32 v80, v89, v98
	v_add_f32_e32 v4, v80, v4
	v_exp_f32_e32 v90, v90
	v_exp_f32_e32 v99, v106
	s_nop 0
	v_add_f32_e32 v80, v90, v99
	v_add_f32_e32 v4, v80, v4
	v_exp_f32_e32 v91, v91
	v_exp_f32_e32 v100, v107
	v_cvt_pk_bf16_f32 v11, v90, v91
	v_add_f32_e32 v80, v91, v100
	v_add_f32_e32 v4, v80, v4
	v_exp_f32_e32 v92, v92
	v_exp_f32_e32 v101, v108
	v_cvt_pk_bf16_f32 v3, v99, v100
	v_add_f32_e32 v80, v92, v101
	v_add_f32_e32 v4, v80, v4
	v_exp_f32_e32 v93, v93
	v_exp_f32_e32 v102, v109
	v_cvt_pk_bf16_f32 v12, v92, v93
	v_add_f32_e32 v80, v93, v102
	v_add_f32_e32 v4, v80, v4
	v_exp_f32_e32 v94, v94
	v_exp_f32_e32 v103, v110
	s_nop 0
	v_add_f32_e32 v80, v94, v103
	v_add_f32_e32 v4, v80, v4
	v_exp_f32_e32 v95, v95
	v_exp_f32_e32 v104, v111
	v_cvt_pk_bf16_f32 v13, v94, v95
	v_add_f32_e32 v80, v95, v104
	v_add_f32_e32 v105, v80, v4
	v_add_f32_e32 v105, v223, v105
.Lfz_join:
	v_mov_b32_e32 v223, v105
	v_cvt_pk_bf16_f32 v80, v2, v5
	v_cvt_pk_bf16_f32 v2, v97, v98
	v_cvt_pk_bf16_f32 v4, v101, v102
	v_cvt_pk_bf16_f32 v5, v103, v104
	v_mov_b32_e32 v15, v224
	ds_read2_b64 v[84:87], v234 offset1:2
	ds_read2_b64 v[88:91], v234 offset0:4 offset1:6
	ds_read2_b64 v[92:95], v234 offset0:8 offset1:10
	ds_read2_b64 v[96:99], v234 offset0:12 offset1:14
	s_waitcnt lgkmcnt(7)
	v_mfma_f32_32x32x16_bf16 v[32:47], v[242:245], v[80:83], v[32:47]
	ds_read2_b64 v[242:245], v235 offset1:2
	s_waitcnt lgkmcnt(7)
	v_mfma_f32_32x32x16_bf16 v[32:47], v[226:229], v[10:13], v[32:47]
	ds_read2_b64 v[226:229], v235 offset0:4 offset1:6
	s_waitcnt lgkmcnt(7)
	v_mfma_f32_32x32x16_bf16 v[32:47], v[230:233], v[6:9], v[32:47]
	ds_read2_b64 v[230:233], v235 offset0:8 offset1:10
	s_waitcnt lgkmcnt(7)
	v_mfma_f32_32x32x16_bf16 v[32:47], v[238:241], v[2:5], v[32:47]
	ds_read2_b64 v[238:241], v235 offset0:12 offset1:14
	s_waitcnt lgkmcnt(7)
	v_mfma_f32_32x32x16_bf16 v[64:79], v[84:87], v[80:83], v[64:79]
	ds_read2_b64 v[84:87], v236 offset1:2
	s_waitcnt lgkmcnt(7)
	v_mfma_f32_32x32x16_bf16 v[64:79], v[88:91], v[10:13], v[64:79]
	ds_read2_b64 v[88:91], v236 offset0:4 offset1:6
	s_waitcnt lgkmcnt(7)
	v_mfma_f32_32x32x16_bf16 v[64:79], v[92:95], v[6:9], v[64:79]
	ds_read2_b64 v[92:95], v236 offset0:8 offset1:10
	s_waitcnt lgkmcnt(7)
	v_mfma_f32_32x32x16_bf16 v[64:79], v[96:99], v[2:5], v[64:79]
	ds_read2_b64 v[96:99], v236 offset0:12 offset1:14
	s_waitcnt lgkmcnt(7)
	v_mfma_f32_32x32x16_bf16 v[48:63], v[242:245], v[80:83], v[48:63]
	s_waitcnt lgkmcnt(6)
	v_mfma_f32_32x32x16_bf16 v[48:63], v[226:229], v[10:13], v[48:63]
	s_waitcnt lgkmcnt(5)
	v_mfma_f32_32x32x16_bf16 v[48:63], v[230:233], v[6:9], v[48:63]
	s_waitcnt lgkmcnt(4)
	v_mfma_f32_32x32x16_bf16 v[48:63], v[238:241], v[2:5], v[48:63]
	s_waitcnt lgkmcnt(3)
	v_mfma_f32_32x32x16_bf16 v[16:31], v[84:87], v[80:83], v[16:31]
	s_waitcnt lgkmcnt(2)
	v_mfma_f32_32x32x16_bf16 v[16:31], v[88:91], v[10:13], v[16:31]
	s_waitcnt lgkmcnt(1)
	v_mfma_f32_32x32x16_bf16 v[16:31], v[92:95], v[6:9], v[16:31]
	s_waitcnt lgkmcnt(0)
	v_mfma_f32_32x32x16_bf16 v[16:31], v[96:99], v[2:5], v[16:31]
	s_branch .LBB0_1928
